# grid barrier: follower workgroups poll the cross-XCD release word directly (skip per-XCD relay hop)
# baseline (speedup 1.0000x reference)
; __device__ __forceinline__ unsigned xb_ld(unsigned* p)              { return __hip_atomic_load(p, __ATOMIC_RELAXED, __HIP_MEMORY_SCOPE_AGENT); }
; __device__ __forceinline__ unsigned xb_add(unsigned* p, unsigned v) { return __hip_atomic_fetch_add(p, v, __ATOMIC_RELAXED, __HIP_MEMORY_SCOPE_AGENT); }
; #define XB_SPIN(cond, bar) do { unsigned _sp = 0; while (cond) { __builtin_amdgcn_s_sleep(1); \
;     if ((++_sp & 255u) == 0u) { if (xb_ld(&(bar)[XB_TMO])) break; if (_sp > XB_SPIN_CAP) { atomicAdd(&(bar)[XB_TMO], 1u); break; } } } } while (0)
; __device__ __forceinline__ void xcd_barrier(const XcdBarrier& b) {
;     ...
;         const unsigned old = xb_add(&bar[XB_XSUB(b.x)], 1u);
;         const unsigned gen = old / nloc;
;         if (old + 1u == (gen + 1u) * nloc) {
;             __builtin_amdgcn_fence(__ATOMIC_RELEASE, "agent");
;             asm volatile("s_waitcnt vmcnt(0)" ::: "memory");
;             const unsigned og = xb_add(&bar[XB_TOP], 1u);
;             const unsigned tg = og / nx;
;             if (og + 1u == (tg + 1u) * nx) xb_add(&bar[XB_TOPGEN], 1u);
;             else XB_SPIN(xb_ld(&bar[XB_TOPGEN]) == tg, bar);
;             __builtin_amdgcn_fence(__ATOMIC_ACQUIRE, "agent");
;             xb_add(&bar[XB_XGEN(b.x)], 1u);
;             asm volatile("s_waitcnt vmcnt(0)" ::: "memory");
;         } else {
;             XB_SPIN(xb_ld(&bar[XB_XGEN(b.x)]) == gen, bar);
.LBB0_262:
	s_or_b64 exec, exec, s[2:3]
	v_cvt_f32_u32_e32 v5, v3
	s_waitcnt vmcnt(0)
	v_readfirstlane_b32 s2, v4
	v_sub_u32_e32 v4, 0, v3
	v_rcp_iflag_f32_e32 v5, v5
	v_add_u32_e32 v6, s2, v2
	v_mul_f32_e32 v5, 0x4f7ffffe, v5
	v_cvt_u32_f32_e32 v5, v5
	v_mul_lo_u32 v2, v4, v5
	v_mul_hi_u32 v2, v5, v2
	v_add_u32_e32 v2, v5, v2
	v_mul_hi_u32 v2, v6, v2
	v_mul_lo_u32 v4, v2, v3
	v_sub_u32_e32 v4, v6, v4
	v_add_u32_e32 v5, 1, v2
	v_sub_u32_e32 v7, v4, v3
	v_cmp_ge_u32_e32 vcc, v4, v3
	s_nop 1
	v_cndmask_b32_e32 v2, v2, v5, vcc
	v_cndmask_b32_e32 v4, v4, v7, vcc
	v_add_u32_e32 v5, 1, v2
	v_cmp_ge_u32_e32 vcc, v4, v3
	v_add_u32_e32 v4, 1, v6
	s_nop 0
	v_cndmask_b32_e32 v2, v2, v5, vcc
	v_mul_lo_u32 v5, v3, v2
	v_add_u32_e32 v3, v5, v3
	v_cmp_ne_u32_e32 vcc, v4, v3
	s_and_saveexec_b64 s[2:3], vcc
	s_xor_b64 s[2:3], exec, s[2:3]
	s_cbranch_execz .LBB0_276
	v_readlane_b32 s4, v252, 54
	v_readlane_b32 s5, v252, 55
	s_waitcnt lgkmcnt(0)
	s_nop 3
	global_load_dword v0, v1, s[4:5] sc1
	s_waitcnt vmcnt(0)
	v_cmp_eq_u32_e32 vcc, v0, v2
	s_and_saveexec_b64 s[4:5], vcc
	s_cbranch_execz .LBB0_275
	s_mov_b32 s20, 1
	s_mov_b64 s[6:7], 0
	s_branch .LBB0_266

; __device__ __forceinline__ unsigned xb_ld(unsigned* p)              { return __hip_atomic_load(p, __ATOMIC_RELAXED, __HIP_MEMORY_SCOPE_AGENT); }
; #define XB_SPIN(cond, bar) do { unsigned _sp = 0; while (cond) { __builtin_amdgcn_s_sleep(1); \
;     if ((++_sp & 255u) == 0u) { if (xb_ld(&(bar)[XB_TMO])) break; if (_sp > XB_SPIN_CAP) { atomicAdd(&(bar)[XB_TMO], 1u); break; } } } } while (0)
; __device__ __forceinline__ void xcd_barrier(const XcdBarrier& b) {
;     ...
;             XB_SPIN(xb_ld(&bar[XB_XGEN(b.x)]) == gen, bar);
.LBB0_268:
	v_readlane_b32 s14, v252, 54
	v_readlane_b32 s15, v252, 55
	s_add_i32 s20, s20, 1
	s_mov_b64 s[16:17], -1
	s_nop 2
	global_load_dword v0, v1, s[14:15] sc1
	s_waitcnt vmcnt(0)
	v_cmp_ne_u32_e32 vcc, v0, v2
	s_orn2_b64 s[14:15], vcc, exec
	s_branch .LBB0_265

; __device__ __forceinline__ unsigned xb_ld(unsigned* p)              { return __hip_atomic_load(p, __ATOMIC_RELAXED, __HIP_MEMORY_SCOPE_AGENT); }
; __device__ __forceinline__ unsigned xb_add(unsigned* p, unsigned v) { return __hip_atomic_fetch_add(p, v, __ATOMIC_RELAXED, __HIP_MEMORY_SCOPE_AGENT); }
; #define XB_SPIN(cond, bar) do { unsigned _sp = 0; while (cond) { __builtin_amdgcn_s_sleep(1); \
;     if ((++_sp & 255u) == 0u) { if (xb_ld(&(bar)[XB_TMO])) break; if (_sp > XB_SPIN_CAP) { atomicAdd(&(bar)[XB_TMO], 1u); break; } } } } while (0)
; __device__ __forceinline__ void xcd_barrier(const XcdBarrier& b) {
;     ...
;         const unsigned old = xb_add(&bar[XB_XSUB(b.x)], 1u);
;         const unsigned gen = old / nloc;
;         if (old + 1u == (gen + 1u) * nloc) {
;             __builtin_amdgcn_fence(__ATOMIC_RELEASE, "agent");
;             asm volatile("s_waitcnt vmcnt(0)" ::: "memory");
;             const unsigned og = xb_add(&bar[XB_TOP], 1u);
;             const unsigned tg = og / nx;
;             if (og + 1u == (tg + 1u) * nx) xb_add(&bar[XB_TOPGEN], 1u);
;             else XB_SPIN(xb_ld(&bar[XB_TOPGEN]) == tg, bar);
;             __builtin_amdgcn_fence(__ATOMIC_ACQUIRE, "agent");
;             xb_add(&bar[XB_XGEN(b.x)], 1u);
;             asm volatile("s_waitcnt vmcnt(0)" ::: "memory");
;         } else {
;             XB_SPIN(xb_ld(&bar[XB_XGEN(b.x)]) == gen, bar);
.LBB0_778:
	s_or_b64 exec, exec, s[2:3]
	v_cvt_f32_u32_e32 v5, v3
	s_waitcnt vmcnt(0)
	v_readfirstlane_b32 s2, v4
	v_sub_u32_e32 v4, 0, v3
	v_rcp_iflag_f32_e32 v5, v5
	v_add_u32_e32 v6, s2, v0
	v_mul_f32_e32 v5, 0x4f7ffffe, v5
	v_cvt_u32_f32_e32 v5, v5
	v_mul_lo_u32 v0, v4, v5
	v_mul_hi_u32 v0, v5, v0
	v_add_u32_e32 v0, v5, v0
	v_mul_hi_u32 v0, v6, v0
	v_mul_lo_u32 v4, v0, v3
	v_sub_u32_e32 v4, v6, v4
	v_add_u32_e32 v5, 1, v0
	v_cmp_ge_u32_e32 vcc, v4, v3
	s_nop 1
	v_cndmask_b32_e32 v0, v0, v5, vcc
	v_sub_u32_e32 v5, v4, v3
	v_cndmask_b32_e32 v4, v4, v5, vcc
	v_add_u32_e32 v5, 1, v0
	v_cmp_ge_u32_e32 vcc, v4, v3
	v_add_u32_e32 v4, 1, v6
	s_nop 0
	v_cndmask_b32_e32 v0, v0, v5, vcc
	v_mul_lo_u32 v5, v3, v0
	v_add_u32_e32 v3, v5, v3
	v_cmp_ne_u32_e32 vcc, v4, v3
	s_and_saveexec_b64 s[2:3], vcc
	s_xor_b64 s[2:3], exec, s[2:3]
	s_cbranch_execz .LBB0_792
	v_readlane_b32 s4, v252, 54
	v_readlane_b32 s5, v252, 55
	s_waitcnt lgkmcnt(0)
	s_nop 3
	global_load_dword v2, v1, s[4:5] sc1
	s_waitcnt vmcnt(0)
	v_cmp_eq_u32_e32 vcc, v2, v0
	s_and_saveexec_b64 s[4:5], vcc
	s_cbranch_execz .LBB0_791
	s_mov_b32 s16, 1
	s_mov_b64 s[6:7], 0
	s_branch .LBB0_782
